# v66 + attention main loops duplicated per half-workgroup (waves 0-3 / 4-7), each copy with its fixed barrier position, no per-tile wave-index tests
# speedup vs baseline: 1.0628x; 1.0024x over previous
; #define SBAR() __builtin_amdgcn_sched_barrier(0)
; DI int v_rd_base(int lane) { return ((lane & 3) << 3) | (((lane >> 2) & 3) << 6) | (((lane >> 4) & 1) << 5) | (((lane >> 5) & 1) << 8); }
; #define ATT_DMA_K(t) do { const bf16_t* kg_ = Kh + (size_t)(t) * 64 * LDK; LAS unsigned char* sb_ = lds + ((t) & 3) * KBUF; \
;     _Pragma("unroll") for (int i_ = 0; i_ < NKP; ++i_) __builtin_amdgcn_global_load_lds((const unsigned*)(kg_ + kgo[i_]), (LAS unsigned*)(sb_ + (wid + 8 * i_) * 1024), 16, 0, 0); } while (0)
; #define ATT_DMA_V(t, vs) do { const bf16_t* vg_ = Vh + (size_t)(t) * 64 * LDV; LAS unsigned char* sb_ = lds + V_OFF + (vs) * SHM_V; \
;     _Pragma("unroll") for (int i_ = 0; i_ < 2; ++i_) __builtin_amdgcn_global_load_lds((const unsigned*)(vg_ + vgo[i_]), (LAS unsigned*)(sb_ + (2 * wid + i_) * 1024), 16, 0, 0); } while (0)
; #define ATT_SEG(t) do { if constexpr (MODE != 0) { if (((t) == tL && tL > 0) || (t) == tR) { const float f_ = (t) == tR ? fR : fL; l_reg *= f_; \
;     _Pragma("unroll") for (int d = 0; d < 4; ++d) _Pragma("unroll") for (int r = 0; r < 16; ++r) o[d][r] *= f_; } } } while (0)
; #define ATT_TOP(N) do { asm volatile("s_waitcnt vmcnt(%0)" :: "n"(N) : "memory"); __builtin_amdgcn_s_barrier(); asm volatile("" ::: "memory"); } while (0)
; template <int DQK, int MODE, int LDQ, int LDK, int LDV> ...
;     ...
;     const int vbase = (int)(unsigned)(size_t)lds + V_OFF + v_rd_base(lane);
;     ...
;     for (int j = 0; j < NT; ++j) {
;         if (j + 2 < NT) ATT_TOP(NKP + 2); else ATT_TOP(0);
;         if (j + 3 < NT) ATT_DMA_K(j + 3);
;         if (j + 2 < NT) ATT_DMA_V(j + 2, v2);
;         ATT_SEG(j); SBAR();
.Lhw_d0_b_n1920:
	s_and_b32 s1, s22, 0x6000
	s_add_i32 m0, s59, s1
	s_lshl_b32 s1, s96, 14
	s_setprio 0
	s_add_i32 s1, s95, s1
	global_load_lds_dwordx4 v100, s[34:35]
	s_add_i32 s2, s1, 0x400
	s_mov_b32 m0, s1
	s_sub_i32 s74, s0, s98
	global_load_lds_dwordx4 v102, s[34:35]
	s_mov_b32 m0, s2
	s_cmp_le_u32 s74, s101
	global_load_lds_dwordx4 v104, s[34:35]
	s_mov_b32 s1, s23
	s_cbranch_scc1 .Lhw_d0_b_dtd0resc

; #define LAS __attribute__((address_space(3)))
; DI void expsum(f32x16& p, float& l_reg, bf16x8& pa0, bf16x8& pa1) {
; #pragma unroll
;     for (int r = 0; r < 16; ++r) p[r] = __builtin_amdgcn_exp2f(p[r]);
;     float ps = 0.f;
; #pragma unroll
;     for (int r = 0; r < 16; ++r) ps += p[r];
;     l_reg += ps; asm volatile("" : "+v"(l_reg));
;     ...
;     ATT_PK4(p, 0, pa0); ATT_PK4(p, 8, pa1);
;     ...
; }
; DI int v_rd_base(int lane) { return ((lane & 3) << 3) | (((lane >> 2) & 3) << 6) | (((lane >> 4) & 1) << 5) | (((lane >> 5) & 1) << 8); }
; template <int OFF> DI s16x4 tr_read(int vb) { s16x4 r; asm volatile("ds_read_b64_tr_b16 %0, %1 offset:%2" : "=&v"(r) : "v"(vb), "i"(OFF) : "memory"); return r; }
; template <int H> DI void v_reads(s16x4* vf, int vb) {
;     vf[0] = tr_read<v_rd_off(0, 2 * H, 0)>(vb); vf[1] = tr_read<v_rd_off(0, 2 * H, 1)>(vb); vf[2] = tr_read<v_rd_off(0, 2 * H + 1, 0)>(vb); vf[3] = tr_read<v_rd_off(0, 2 * H + 1, 1)>(vb);
;     vf[4] = tr_read<v_rd_off(1, 2 * H, 0)>(vb); vf[5] = tr_read<v_rd_off(1, 2 * H, 1)>(vb); vf[6] = tr_read<v_rd_off(1, 2 * H + 1, 0)>(vb); vf[7] = tr_read<v_rd_off(1, 2 * H + 1, 1)>(vb);
;     vf[8] = tr_read<v_rd_off(2, 2 * H, 0)>(vb); vf[9] = tr_read<v_rd_off(2, 2 * H, 1)>(vb); vf[10] = tr_read<v_rd_off(2, 2 * H + 1, 0)>(vb); vf[11] = tr_read<v_rd_off(2, 2 * H + 1, 1)>(vb);
;     vf[12] = tr_read<v_rd_off(3, 2 * H, 0)>(vb); vf[13] = tr_read<v_rd_off(3, 2 * H, 1)>(vb); vf[14] = tr_read<v_rd_off(3, 2 * H + 1, 0)>(vb); vf[15] = tr_read<v_rd_off(3, 2 * H + 1, 1)>(vb);
; }
; DI void pv_mma(f32x16* o, const s16x4* vf, bf16x8 pa0, bf16x8 pa1) {
;     ...
; #pragma unroll
;     for (int d0 = 0; d0 < 4; ++d0) {
;         o[d0] = __builtin_amdgcn_mfma_f32_32x32x16_bf16(pa0, ATT_PK(vf[4 * d0], vf[4 * d0 + 1]), o[d0], 0, 0, 0);
;         o[d0] = __builtin_amdgcn_mfma_f32_32x32x16_bf16(pa1, ATT_PK(vf[4 * d0 + 2], vf[4 * d0 + 3]), o[d0], 0, 0, 0); }
;     ...
; }
; template <int DQK, int D0A, int D0B> DI void k_reads(bf16x8* kf, const LAS unsigned char* Ks, int half, int r32, int hi) {
; #pragma unroll
;     for (int d0 = D0A; d0 < D0B; ++d0) kf[d0 - D0A] = *(const LAS bf16x8*)(Ks + half * (32 * DQK * 2) + kswz<DQK>(r32, (d0 * 16 + hi * 8) * 2));
; }
; template <int D0A, int D0B> DI void qk_mma(f32x16& p, const bf16x8* kf, const bf16x8* qr) {
; #pragma unroll
;     for (int d0 = D0A; d0 < D0B; ++d0) {
.Lhw_d0_b_n1924:
	s_add_i32 s3, s22, 0xffffc000
	s_and_b32 s3, s3, 0x6000
	v_add_u32_e32 v196, s3, v107
	v_add_u32_e32 v197, s3, v108
	v_add_u32_e32 v198, s3, v109
	v_add_u32_e32 v199, s3, v110
	ds_read_b128 v[124:127], v196
	ds_read_b128 v[132:135], v197
	ds_read_b128 v[136:139], v198
	ds_read_b128 v[140:143], v199
	ds_read_b64_tr_b16 v[144:145], v121 offset:0x2000
	ds_read_b64_tr_b16 v[146:147], v121 offset:0x2800
	ds_read_b64_tr_b16 v[148:149], v121 offset:0x3000
	ds_read_b64_tr_b16 v[150:151], v121 offset:0x3800
	ds_read_b64_tr_b16 v[152:153], v121 offset:0x2200
	ds_read_b64_tr_b16 v[154:155], v121 offset:0x2a00
	ds_read_b64_tr_b16 v[156:157], v121 offset:0x3200
	ds_read_b64_tr_b16 v[158:159], v121 offset:0x3a00
	ds_read_b64_tr_b16 v[162:163], v121 offset:0x2400
	ds_read_b64_tr_b16 v[164:165], v121 offset:0x2c00
	ds_read_b64_tr_b16 v[166:167], v121 offset:0x3400
	ds_read_b64_tr_b16 v[168:169], v121 offset:0x3c00
	ds_read_b64_tr_b16 v[170:171], v121 offset:0x2600
	ds_read_b64_tr_b16 v[172:173], v121 offset:0x2e00
	ds_read_b64_tr_b16 v[174:175], v121 offset:0x3600
	ds_read_b64_tr_b16 v[176:177], v121 offset:0x3e00
	s_setprio 2
	v_exp_f32_e32 v64, v64
	v_exp_f32_e32 v65, v65
	v_exp_f32_e32 v66, v66
	v_exp_f32_e32 v67, v67
	v_exp_f32_e32 v68, v68
	v_exp_f32_e32 v69, v69
	v_add_f32_e32 v121, v65, v64
	v_exp_f32_e32 v70, v70
	v_add_f32_e32 v121, v66, v121
	v_exp_f32_e32 v71, v71
	v_add_f32_e32 v121, v67, v121
	v_exp_f32_e32 v72, v72
	v_add_f32_e32 v121, v68, v121
	v_exp_f32_e32 v73, v73
	v_add_f32_e32 v121, v69, v121
	v_exp_f32_e32 v74, v74
	v_add_f32_e32 v121, v70, v121
	v_exp_f32_e32 v75, v75
	v_add_f32_e32 v121, v71, v121
	v_exp_f32_e32 v76, v76
	v_add_f32_e32 v121, v72, v121
	v_exp_f32_e32 v77, v77
	v_add_f32_e32 v121, v73, v121
	v_exp_f32_e32 v78, v78
	v_add_f32_e32 v121, v74, v121
	v_exp_f32_e32 v79, v79
	v_add_f32_e32 v121, v75, v121
	v_add_f32_e32 v121, v76, v121
	v_add_f32_e32 v121, v77, v121
	v_add_f32_e32 v121, v78, v121
	v_add_f32_e32 v121, v79, v121
	v_add_f32_e32 v120, v120, v121
	v_cvt_pk_bf16_f32 v64, v64, v65
	v_cvt_pk_bf16_f32 v65, v66, v67
	v_cvt_pk_bf16_f32 v66, v68, v69
	v_cvt_pk_bf16_f32 v67, v70, v71
	v_cvt_pk_bf16_f32 v68, v72, v73
	v_cvt_pk_bf16_f32 v69, v74, v75
	v_cvt_pk_bf16_f32 v70, v76, v77
	v_cvt_pk_bf16_f32 v71, v78, v79
	s_nop 0
	v_permlane32_swap_b32_e32 v64, v66
	v_permlane32_swap_b32_e32 v65, v67
	v_permlane32_swap_b32_e32 v68, v70
	v_permlane32_swap_b32_e32 v69, v71
	s_waitcnt lgkmcnt(0)
	s_setprio 1
	s_waitcnt vmcnt(3)
	s_barrier
	v_mfma_f32_32x32x16_bf16 v[0:15], v[64:67], v[144:147], v[0:15]
	s_sub_i32 s74, s0, s55
	s_cmp_lt_u32 s74, s100
	v_mfma_f32_32x32x16_bf16 v[48:63], v[64:67], v[152:155], v[48:63]
	v_mfma_f32_32x32x16_bf16 v[32:47], v[64:67], v[162:165], v[32:47]
	v_mfma_f32_32x32x16_bf16 v[16:31], v[64:67], v[170:173], v[16:31]
	v_mfma_f32_32x32x16_bf16 v[0:15], v[68:71], v[148:151], v[0:15]
	v_mfma_f32_32x32x16_bf16 v[48:63], v[68:71], v[156:159], v[48:63]
	v_mfma_f32_32x32x16_bf16 v[32:47], v[68:71], v[166:169], v[32:47]
	v_mfma_f32_32x32x16_bf16 v[16:31], v[68:71], v[174:177], v[16:31]
	v_mfma_f32_32x32x16_bf16 v[64:79], v[124:127], v[92:95], 0
	v_mfma_f32_32x32x16_bf16 v[64:79], v[132:135], v[88:91], v[64:79]
	v_mfma_f32_32x32x16_bf16 v[64:79], v[136:139], v[84:87], v[64:79]
	v_mfma_f32_32x32x16_bf16 v[64:79], v[140:143], v[80:83], v[64:79]
	s_cbranch_scc1 .Lhw_d0_b_dtd0bias2

; #define SBAR() __builtin_amdgcn_sched_barrier(0)
; DI int v_rd_base(int lane) { return ((lane & 3) << 3) | (((lane >> 2) & 3) << 6) | (((lane >> 4) & 1) << 5) | (((lane >> 5) & 1) << 8); }
; #define ATT_DMA_K(t) do { const bf16_t* kg_ = Kh + (size_t)(t) * 64 * LDK; LAS unsigned char* sb_ = lds + ((t) & 3) * KBUF; \
;     _Pragma("unroll") for (int i_ = 0; i_ < NKP; ++i_) __builtin_amdgcn_global_load_lds((const unsigned*)(kg_ + kgo[i_]), (LAS unsigned*)(sb_ + (wid + 8 * i_) * 1024), 16, 0, 0); } while (0)
; #define ATT_DMA_V(t, vs) do { const bf16_t* vg_ = Vh + (size_t)(t) * 64 * LDV; LAS unsigned char* sb_ = lds + V_OFF + (vs) * SHM_V; \
;     _Pragma("unroll") for (int i_ = 0; i_ < 2; ++i_) __builtin_amdgcn_global_load_lds((const unsigned*)(vg_ + vgo[i_]), (LAS unsigned*)(sb_ + (2 * wid + i_) * 1024), 16, 0, 0); } while (0)
; #define ATT_SEG(t) do { if constexpr (MODE != 0) { if (((t) == tL && tL > 0) || (t) == tR) { const float f_ = (t) == tR ? fR : fL; l_reg *= f_; \
;     _Pragma("unroll") for (int d = 0; d < 4; ++d) _Pragma("unroll") for (int r = 0; r < 16; ++r) o[d][r] *= f_; } } } while (0)
; #define ATT_TOP(N) do { asm volatile("s_waitcnt vmcnt(%0)" :: "n"(N) : "memory"); __builtin_amdgcn_s_barrier(); asm volatile("" ::: "memory"); } while (0)
; template <int DQK, int MODE, int LDQ, int LDK, int LDV> ...
;     ...
;     const int vbase = (int)(unsigned)(size_t)lds + V_OFF + v_rd_base(lane);
;     ...
;     for (int j = 0; j < NT; ++j) {
;         if (j + 2 < NT) ATT_TOP(NKP + 2); else ATT_TOP(0);
;         if (j + 3 < NT) ATT_DMA_K(j + 3);
;         if (j + 2 < NT) ATT_DMA_V(j + 2, v2);
;         ATT_SEG(j); SBAR();
.LBB0_1920:
	s_and_b32 s1, s22, 0x6000
	s_add_i32 m0, s59, s1
	s_lshl_b32 s1, s96, 14
	s_waitcnt vmcnt(3)
	s_barrier
	s_setprio 0
	s_add_i32 s1, s95, s1
	global_load_lds_dwordx4 v100, s[34:35]
	s_add_i32 s2, s1, 0x400
	s_mov_b32 m0, s1
	s_sub_i32 s74, s0, s98
	global_load_lds_dwordx4 v102, s[34:35]
	s_mov_b32 m0, s2
	s_cmp_le_u32 s74, s101
	global_load_lds_dwordx4 v104, s[34:35]
	s_mov_b32 s1, s23
	s_cbranch_scc1 .Ldt_d0_resc

; #define LAS __attribute__((address_space(3)))
; DI void expsum(f32x16& p, float& l_reg, bf16x8& pa0, bf16x8& pa1) {
; #pragma unroll
;     for (int r = 0; r < 16; ++r) p[r] = __builtin_amdgcn_exp2f(p[r]);
;     float ps = 0.f;
; #pragma unroll
;     for (int r = 0; r < 16; ++r) ps += p[r];
;     l_reg += ps; asm volatile("" : "+v"(l_reg));
;     ...
;     ATT_PK4(p, 0, pa0); ATT_PK4(p, 8, pa1);
;     ...
; }
; DI int v_rd_base(int lane) { return ((lane & 3) << 3) | (((lane >> 2) & 3) << 6) | (((lane >> 4) & 1) << 5) | (((lane >> 5) & 1) << 8); }
; template <int OFF> DI s16x4 tr_read(int vb) { s16x4 r; asm volatile("ds_read_b64_tr_b16 %0, %1 offset:%2" : "=&v"(r) : "v"(vb), "i"(OFF) : "memory"); return r; }
; template <int H> DI void v_reads(s16x4* vf, int vb) {
;     vf[0] = tr_read<v_rd_off(0, 2 * H, 0)>(vb); vf[1] = tr_read<v_rd_off(0, 2 * H, 1)>(vb); vf[2] = tr_read<v_rd_off(0, 2 * H + 1, 0)>(vb); vf[3] = tr_read<v_rd_off(0, 2 * H + 1, 1)>(vb);
;     vf[4] = tr_read<v_rd_off(1, 2 * H, 0)>(vb); vf[5] = tr_read<v_rd_off(1, 2 * H, 1)>(vb); vf[6] = tr_read<v_rd_off(1, 2 * H + 1, 0)>(vb); vf[7] = tr_read<v_rd_off(1, 2 * H + 1, 1)>(vb);
;     vf[8] = tr_read<v_rd_off(2, 2 * H, 0)>(vb); vf[9] = tr_read<v_rd_off(2, 2 * H, 1)>(vb); vf[10] = tr_read<v_rd_off(2, 2 * H + 1, 0)>(vb); vf[11] = tr_read<v_rd_off(2, 2 * H + 1, 1)>(vb);
;     vf[12] = tr_read<v_rd_off(3, 2 * H, 0)>(vb); vf[13] = tr_read<v_rd_off(3, 2 * H, 1)>(vb); vf[14] = tr_read<v_rd_off(3, 2 * H + 1, 0)>(vb); vf[15] = tr_read<v_rd_off(3, 2 * H + 1, 1)>(vb);
; }
; DI void pv_mma(f32x16* o, const s16x4* vf, bf16x8 pa0, bf16x8 pa1) {
;     ...
; #pragma unroll
;     for (int d0 = 0; d0 < 4; ++d0) {
;         o[d0] = __builtin_amdgcn_mfma_f32_32x32x16_bf16(pa0, ATT_PK(vf[4 * d0], vf[4 * d0 + 1]), o[d0], 0, 0, 0);
;         o[d0] = __builtin_amdgcn_mfma_f32_32x32x16_bf16(pa1, ATT_PK(vf[4 * d0 + 2], vf[4 * d0 + 3]), o[d0], 0, 0, 0); }
;     ...
; }
; template <int DQK, int D0A, int D0B> DI void k_reads(bf16x8* kf, const LAS unsigned char* Ks, int half, int r32, int hi) {
; #pragma unroll
;     for (int d0 = D0A; d0 < D0B; ++d0) kf[d0 - D0A] = *(const LAS bf16x8*)(Ks + half * (32 * DQK * 2) + kswz<DQK>(r32, (d0 * 16 + hi * 8) * 2));
; }
; template <int D0A, int D0B> DI void qk_mma(f32x16& p, const bf16x8* kf, const bf16x8* qr) {
; #pragma unroll
;     for (int d0 = D0A; d0 < D0B; ++d0) {
.LBB0_1924:
	s_add_i32 s3, s22, 0xffffc000
	s_and_b32 s3, s3, 0x6000
	v_add_u32_e32 v196, s3, v107
	v_add_u32_e32 v197, s3, v108
	v_add_u32_e32 v198, s3, v109
	v_add_u32_e32 v199, s3, v110
	ds_read_b128 v[124:127], v196
	ds_read_b128 v[132:135], v197
	ds_read_b128 v[136:139], v198
	ds_read_b128 v[140:143], v199
	ds_read_b64_tr_b16 v[144:145], v121 offset:0x2000
	ds_read_b64_tr_b16 v[146:147], v121 offset:0x2800
	ds_read_b64_tr_b16 v[148:149], v121 offset:0x3000
	ds_read_b64_tr_b16 v[150:151], v121 offset:0x3800
	ds_read_b64_tr_b16 v[152:153], v121 offset:0x2200
	ds_read_b64_tr_b16 v[154:155], v121 offset:0x2a00
	ds_read_b64_tr_b16 v[156:157], v121 offset:0x3200
	ds_read_b64_tr_b16 v[158:159], v121 offset:0x3a00
	ds_read_b64_tr_b16 v[162:163], v121 offset:0x2400
	ds_read_b64_tr_b16 v[164:165], v121 offset:0x2c00
	ds_read_b64_tr_b16 v[166:167], v121 offset:0x3400
	ds_read_b64_tr_b16 v[168:169], v121 offset:0x3c00
	ds_read_b64_tr_b16 v[170:171], v121 offset:0x2600
	ds_read_b64_tr_b16 v[172:173], v121 offset:0x2e00
	ds_read_b64_tr_b16 v[174:175], v121 offset:0x3600
	ds_read_b64_tr_b16 v[176:177], v121 offset:0x3e00
	s_setprio 2
	v_exp_f32_e32 v64, v64
	v_exp_f32_e32 v65, v65
	v_exp_f32_e32 v66, v66
	v_exp_f32_e32 v67, v67
	v_exp_f32_e32 v68, v68
	v_exp_f32_e32 v69, v69
	v_add_f32_e32 v121, v65, v64
	v_exp_f32_e32 v70, v70
	v_add_f32_e32 v121, v66, v121
	v_exp_f32_e32 v71, v71
	v_add_f32_e32 v121, v67, v121
	v_exp_f32_e32 v72, v72
	v_add_f32_e32 v121, v68, v121
	v_exp_f32_e32 v73, v73
	v_add_f32_e32 v121, v69, v121
	v_exp_f32_e32 v74, v74
	v_add_f32_e32 v121, v70, v121
	v_exp_f32_e32 v75, v75
	v_add_f32_e32 v121, v71, v121
	v_exp_f32_e32 v76, v76
	v_add_f32_e32 v121, v72, v121
	v_exp_f32_e32 v77, v77
	v_add_f32_e32 v121, v73, v121
	v_exp_f32_e32 v78, v78
	v_add_f32_e32 v121, v74, v121
	v_exp_f32_e32 v79, v79
	v_add_f32_e32 v121, v75, v121
	v_add_f32_e32 v121, v76, v121
	v_add_f32_e32 v121, v77, v121
	v_add_f32_e32 v121, v78, v121
	v_add_f32_e32 v121, v79, v121
	v_add_f32_e32 v120, v120, v121
	v_cvt_pk_bf16_f32 v64, v64, v65
	v_cvt_pk_bf16_f32 v65, v66, v67
	v_cvt_pk_bf16_f32 v66, v68, v69
	v_cvt_pk_bf16_f32 v67, v70, v71
	v_cvt_pk_bf16_f32 v68, v72, v73
	v_cvt_pk_bf16_f32 v69, v74, v75
	v_cvt_pk_bf16_f32 v70, v76, v77
	v_cvt_pk_bf16_f32 v71, v78, v79
	s_nop 0
	v_permlane32_swap_b32_e32 v64, v66
	v_permlane32_swap_b32_e32 v65, v67
	v_permlane32_swap_b32_e32 v68, v70
	v_permlane32_swap_b32_e32 v69, v71
	s_waitcnt lgkmcnt(0)
	s_setprio 1
	v_mfma_f32_32x32x16_bf16 v[0:15], v[64:67], v[144:147], v[0:15]
	s_sub_i32 s74, s0, s55
	s_cmp_lt_u32 s74, s100
	v_mfma_f32_32x32x16_bf16 v[48:63], v[64:67], v[152:155], v[48:63]
	v_mfma_f32_32x32x16_bf16 v[32:47], v[64:67], v[162:165], v[32:47]
	v_mfma_f32_32x32x16_bf16 v[16:31], v[64:67], v[170:173], v[16:31]
	v_mfma_f32_32x32x16_bf16 v[0:15], v[68:71], v[148:151], v[0:15]
	v_mfma_f32_32x32x16_bf16 v[48:63], v[68:71], v[156:159], v[48:63]
	v_mfma_f32_32x32x16_bf16 v[32:47], v[68:71], v[166:169], v[32:47]
	v_mfma_f32_32x32x16_bf16 v[16:31], v[68:71], v[174:177], v[16:31]
	v_mfma_f32_32x32x16_bf16 v[64:79], v[124:127], v[92:95], 0
	v_mfma_f32_32x32x16_bf16 v[64:79], v[132:135], v[88:91], v[64:79]
	v_mfma_f32_32x32x16_bf16 v[64:79], v[136:139], v[84:87], v[64:79]
	v_mfma_f32_32x32x16_bf16 v[64:79], v[140:143], v[80:83], v[64:79]
	s_cbranch_scc1 .Ldt_d0_bias2

; #define SBAR() __builtin_amdgcn_sched_barrier(0)
; DI int v_rd_base(int lane) { return ((lane & 3) << 3) | (((lane >> 2) & 3) << 6) | (((lane >> 4) & 1) << 5) | (((lane >> 5) & 1) << 8); }
; #define ATT_DMA_K(t) do { const bf16_t* kg_ = Kh + (size_t)(t) * 64 * LDK; LAS unsigned char* sb_ = lds + ((t) & 3) * KBUF; \
;     _Pragma("unroll") for (int i_ = 0; i_ < NKP; ++i_) __builtin_amdgcn_global_load_lds((const unsigned*)(kg_ + kgo[i_]), (LAS unsigned*)(sb_ + (wid + 8 * i_) * 1024), 16, 0, 0); } while (0)
; #define ATT_DMA_V(t, vs) do { const bf16_t* vg_ = Vh + (size_t)(t) * 64 * LDV; LAS unsigned char* sb_ = lds + V_OFF + (vs) * SHM_V; \
;     _Pragma("unroll") for (int i_ = 0; i_ < 2; ++i_) __builtin_amdgcn_global_load_lds((const unsigned*)(vg_ + vgo[i_]), (LAS unsigned*)(sb_ + (2 * wid + i_) * 1024), 16, 0, 0); } while (0)
; #define ATT_SEG(t) do { if constexpr (MODE != 0) { if (((t) == tL && tL > 0) || (t) == tR) { const float f_ = (t) == tR ? fR : fL; l_reg *= f_; \
;     _Pragma("unroll") for (int d = 0; d < 4; ++d) _Pragma("unroll") for (int r = 0; r < 16; ++r) o[d][r] *= f_; } } } while (0)
; #define ATT_TOP(N) do { asm volatile("s_waitcnt vmcnt(%0)" :: "n"(N) : "memory"); __builtin_amdgcn_s_barrier(); asm volatile("" ::: "memory"); } while (0)
; template <int DQK, int MODE, int LDQ, int LDK, int LDV> ...
;     ...
;     const int vbase = (int)(unsigned)(size_t)lds + V_OFF + v_rd_base(lane);
;     ...
;     for (int j = 0; j < NT; ++j) {
;         if (j + 2 < NT) ATT_TOP(NKP + 2); else ATT_TOP(0);
;         if (j + 3 < NT) ATT_DMA_K(j + 3);
;         if (j + 2 < NT) ATT_DMA_V(j + 2, v2);
;         ATT_SEG(j); SBAR();
.Lhw_d1_b_n1951:
	s_and_b32 s2, s22, 0x6000
	s_add_i32 m0, s94, s2
	s_lshl_b32 s2, s1, 14
	s_setprio 0
	s_add_i32 s2, s48, s2
	global_load_lds_dwordx4 v100, s[34:35]
	s_add_i32 s3, s2, 0x400
	s_mov_b32 m0, s2
	s_sub_i32 s74, s0, s98
	global_load_lds_dwordx4 v102, s[34:35]
	s_mov_b32 m0, s3
	s_cmp_le_u32 s74, s101
	global_load_lds_dwordx4 v104, s[34:35]
	s_mov_b32 s23, s62
	s_cbranch_scc1 .Lhw_d1_b_dtd1resc

; #define LAS __attribute__((address_space(3)))
; DI void expsum(f32x16& p, float& l_reg, bf16x8& pa0, bf16x8& pa1) {
; #pragma unroll
;     for (int r = 0; r < 16; ++r) p[r] = __builtin_amdgcn_exp2f(p[r]);
;     float ps = 0.f;
; #pragma unroll
;     for (int r = 0; r < 16; ++r) ps += p[r];
;     l_reg += ps; asm volatile("" : "+v"(l_reg));
;     ...
;     ATT_PK4(p, 0, pa0); ATT_PK4(p, 8, pa1);
;     ...
; }
; DI int v_rd_base(int lane) { return ((lane & 3) << 3) | (((lane >> 2) & 3) << 6) | (((lane >> 4) & 1) << 5) | (((lane >> 5) & 1) << 8); }
; template <int OFF> DI s16x4 tr_read(int vb) { s16x4 r; asm volatile("ds_read_b64_tr_b16 %0, %1 offset:%2" : "=&v"(r) : "v"(vb), "i"(OFF) : "memory"); return r; }
; template <int H> DI void v_reads(s16x4* vf, int vb) {
;     vf[0] = tr_read<v_rd_off(0, 2 * H, 0)>(vb); vf[1] = tr_read<v_rd_off(0, 2 * H, 1)>(vb); vf[2] = tr_read<v_rd_off(0, 2 * H + 1, 0)>(vb); vf[3] = tr_read<v_rd_off(0, 2 * H + 1, 1)>(vb);
;     vf[4] = tr_read<v_rd_off(1, 2 * H, 0)>(vb); vf[5] = tr_read<v_rd_off(1, 2 * H, 1)>(vb); vf[6] = tr_read<v_rd_off(1, 2 * H + 1, 0)>(vb); vf[7] = tr_read<v_rd_off(1, 2 * H + 1, 1)>(vb);
;     vf[8] = tr_read<v_rd_off(2, 2 * H, 0)>(vb); vf[9] = tr_read<v_rd_off(2, 2 * H, 1)>(vb); vf[10] = tr_read<v_rd_off(2, 2 * H + 1, 0)>(vb); vf[11] = tr_read<v_rd_off(2, 2 * H + 1, 1)>(vb);
;     vf[12] = tr_read<v_rd_off(3, 2 * H, 0)>(vb); vf[13] = tr_read<v_rd_off(3, 2 * H, 1)>(vb); vf[14] = tr_read<v_rd_off(3, 2 * H + 1, 0)>(vb); vf[15] = tr_read<v_rd_off(3, 2 * H + 1, 1)>(vb);
; }
; DI void pv_mma(f32x16* o, const s16x4* vf, bf16x8 pa0, bf16x8 pa1) {
;     ...
; #pragma unroll
;     for (int d0 = 0; d0 < 4; ++d0) {
;         o[d0] = __builtin_amdgcn_mfma_f32_32x32x16_bf16(pa0, ATT_PK(vf[4 * d0], vf[4 * d0 + 1]), o[d0], 0, 0, 0);
;         o[d0] = __builtin_amdgcn_mfma_f32_32x32x16_bf16(pa1, ATT_PK(vf[4 * d0 + 2], vf[4 * d0 + 3]), o[d0], 0, 0, 0); }
;     ...
; }
; template <int DQK, int D0A, int D0B> DI void k_reads(bf16x8* kf, const LAS unsigned char* Ks, int half, int r32, int hi) {
; #pragma unroll
;     for (int d0 = D0A; d0 < D0B; ++d0) kf[d0 - D0A] = *(const LAS bf16x8*)(Ks + half * (32 * DQK * 2) + kswz<DQK>(r32, (d0 * 16 + hi * 8) * 2));
; }
; template <int D0A, int D0B> DI void qk_mma(f32x16& p, const bf16x8* kf, const bf16x8* qr) {
; #pragma unroll
;     for (int d0 = D0A; d0 < D0B; ++d0) {
.Lhw_d1_b_n1955:
	s_add_i32 s3, s22, 0xffffc000
	s_and_b32 s3, s3, 0x6000
	v_add_u32_e32 v196, s3, v107
	v_add_u32_e32 v197, s3, v108
	v_add_u32_e32 v198, s3, v109
	v_add_u32_e32 v199, s3, v110
	ds_read_b128 v[124:127], v196
	ds_read_b128 v[132:135], v197
	ds_read_b128 v[136:139], v198
	ds_read_b128 v[140:143], v199
	ds_read_b64_tr_b16 v[144:145], v121 offset:0x2000
	ds_read_b64_tr_b16 v[146:147], v121 offset:0x2800
	ds_read_b64_tr_b16 v[148:149], v121 offset:0x3000
	ds_read_b64_tr_b16 v[150:151], v121 offset:0x3800
	ds_read_b64_tr_b16 v[152:153], v121 offset:0x2200
	ds_read_b64_tr_b16 v[154:155], v121 offset:0x2a00
	ds_read_b64_tr_b16 v[156:157], v121 offset:0x3200
	ds_read_b64_tr_b16 v[158:159], v121 offset:0x3a00
	ds_read_b64_tr_b16 v[162:163], v121 offset:0x2400
	ds_read_b64_tr_b16 v[164:165], v121 offset:0x2c00
	ds_read_b64_tr_b16 v[166:167], v121 offset:0x3400
	ds_read_b64_tr_b16 v[168:169], v121 offset:0x3c00
	ds_read_b64_tr_b16 v[170:171], v121 offset:0x2600
	ds_read_b64_tr_b16 v[172:173], v121 offset:0x2e00
	ds_read_b64_tr_b16 v[174:175], v121 offset:0x3600
	ds_read_b64_tr_b16 v[176:177], v121 offset:0x3e00
	s_setprio 2
	v_exp_f32_e32 v64, v64
	v_exp_f32_e32 v65, v65
	v_exp_f32_e32 v66, v66
	v_exp_f32_e32 v67, v67
	v_exp_f32_e32 v68, v68
	v_exp_f32_e32 v69, v69
	v_add_f32_e32 v121, v65, v64
	v_exp_f32_e32 v70, v70
	v_add_f32_e32 v121, v66, v121
	v_exp_f32_e32 v71, v71
	v_add_f32_e32 v121, v67, v121
	v_exp_f32_e32 v72, v72
	v_add_f32_e32 v121, v68, v121
	v_exp_f32_e32 v73, v73
	v_add_f32_e32 v121, v69, v121
	v_exp_f32_e32 v74, v74
	v_add_f32_e32 v121, v70, v121
	v_exp_f32_e32 v75, v75
	v_add_f32_e32 v121, v71, v121
	v_exp_f32_e32 v76, v76
	v_add_f32_e32 v121, v72, v121
	v_exp_f32_e32 v77, v77
	v_add_f32_e32 v121, v73, v121
	v_exp_f32_e32 v78, v78
	v_add_f32_e32 v121, v74, v121
	v_exp_f32_e32 v79, v79
	v_add_f32_e32 v121, v75, v121
	v_add_f32_e32 v121, v76, v121
	v_add_f32_e32 v121, v77, v121
	v_add_f32_e32 v121, v78, v121
	v_add_f32_e32 v121, v79, v121
	v_add_f32_e32 v120, v120, v121
	v_cvt_pk_bf16_f32 v64, v64, v65
	v_cvt_pk_bf16_f32 v65, v66, v67
	v_cvt_pk_bf16_f32 v66, v68, v69
	v_cvt_pk_bf16_f32 v67, v70, v71
	v_cvt_pk_bf16_f32 v68, v72, v73
	v_cvt_pk_bf16_f32 v69, v74, v75
	v_cvt_pk_bf16_f32 v70, v76, v77
	v_cvt_pk_bf16_f32 v71, v78, v79
	s_nop 0
	v_permlane32_swap_b32_e32 v64, v66
	v_permlane32_swap_b32_e32 v65, v67
	v_permlane32_swap_b32_e32 v68, v70
	v_permlane32_swap_b32_e32 v69, v71
	s_waitcnt lgkmcnt(0)
	s_setprio 1
	s_waitcnt vmcnt(3)
	s_barrier
	v_mfma_f32_32x32x16_bf16 v[0:15], v[64:67], v[144:147], v[0:15]
	s_sub_i32 s74, s0, s47
	s_cmp_lt_u32 s74, s100
	v_mfma_f32_32x32x16_bf16 v[48:63], v[64:67], v[152:155], v[48:63]
	v_mfma_f32_32x32x16_bf16 v[16:31], v[64:67], v[162:165], v[16:31]
	v_mfma_f32_32x32x16_bf16 v[32:47], v[64:67], v[170:173], v[32:47]
	v_mfma_f32_32x32x16_bf16 v[0:15], v[68:71], v[148:151], v[0:15]
	v_mfma_f32_32x32x16_bf16 v[48:63], v[68:71], v[156:159], v[48:63]
	v_mfma_f32_32x32x16_bf16 v[16:31], v[68:71], v[166:169], v[16:31]
	v_mfma_f32_32x32x16_bf16 v[32:47], v[68:71], v[174:177], v[32:47]
	v_mfma_f32_32x32x16_bf16 v[64:79], v[124:127], v[92:95], 0
	v_mfma_f32_32x32x16_bf16 v[64:79], v[132:135], v[88:91], v[64:79]
	v_mfma_f32_32x32x16_bf16 v[64:79], v[136:139], v[84:87], v[64:79]
	v_mfma_f32_32x32x16_bf16 v[64:79], v[140:143], v[80:83], v[64:79]
	s_cbranch_scc1 .Lhw_d1_b_dtd1bias2

; #define SBAR() __builtin_amdgcn_sched_barrier(0)
; DI int v_rd_base(int lane) { return ((lane & 3) << 3) | (((lane >> 2) & 3) << 6) | (((lane >> 4) & 1) << 5) | (((lane >> 5) & 1) << 8); }
; #define ATT_DMA_K(t) do { const bf16_t* kg_ = Kh + (size_t)(t) * 64 * LDK; LAS unsigned char* sb_ = lds + ((t) & 3) * KBUF; \
;     _Pragma("unroll") for (int i_ = 0; i_ < NKP; ++i_) __builtin_amdgcn_global_load_lds((const unsigned*)(kg_ + kgo[i_]), (LAS unsigned*)(sb_ + (wid + 8 * i_) * 1024), 16, 0, 0); } while (0)
; #define ATT_DMA_V(t, vs) do { const bf16_t* vg_ = Vh + (size_t)(t) * 64 * LDV; LAS unsigned char* sb_ = lds + V_OFF + (vs) * SHM_V; \
;     _Pragma("unroll") for (int i_ = 0; i_ < 2; ++i_) __builtin_amdgcn_global_load_lds((const unsigned*)(vg_ + vgo[i_]), (LAS unsigned*)(sb_ + (2 * wid + i_) * 1024), 16, 0, 0); } while (0)
; #define ATT_SEG(t) do { if constexpr (MODE != 0) { if (((t) == tL && tL > 0) || (t) == tR) { const float f_ = (t) == tR ? fR : fL; l_reg *= f_; \
;     _Pragma("unroll") for (int d = 0; d < 4; ++d) _Pragma("unroll") for (int r = 0; r < 16; ++r) o[d][r] *= f_; } } } while (0)
; #define ATT_TOP(N) do { asm volatile("s_waitcnt vmcnt(%0)" :: "n"(N) : "memory"); __builtin_amdgcn_s_barrier(); asm volatile("" ::: "memory"); } while (0)
; template <int DQK, int MODE, int LDQ, int LDK, int LDV> ...
;     ...
;     const int vbase = (int)(unsigned)(size_t)lds + V_OFF + v_rd_base(lane);
;     ...
;     for (int j = 0; j < NT; ++j) {
;         if (j + 2 < NT) ATT_TOP(NKP + 2); else ATT_TOP(0);
;         if (j + 3 < NT) ATT_DMA_K(j + 3);
;         if (j + 2 < NT) ATT_DMA_V(j + 2, v2);
;         ATT_SEG(j); SBAR();
.LBB0_1951:
	s_and_b32 s2, s22, 0x6000
	s_add_i32 m0, s94, s2
	s_lshl_b32 s2, s1, 14
	s_waitcnt vmcnt(3)
	s_barrier
	s_setprio 0
	s_add_i32 s2, s48, s2
	global_load_lds_dwordx4 v100, s[34:35]
	s_add_i32 s3, s2, 0x400
	s_mov_b32 m0, s2
	s_sub_i32 s74, s0, s98
	global_load_lds_dwordx4 v102, s[34:35]
	s_mov_b32 m0, s3
	s_cmp_le_u32 s74, s101
	global_load_lds_dwordx4 v104, s[34:35]
	s_mov_b32 s23, s62
	s_cbranch_scc1 .Ldt_d1_resc

; #define LAS __attribute__((address_space(3)))
; DI void expsum(f32x16& p, float& l_reg, bf16x8& pa0, bf16x8& pa1) {
; #pragma unroll
;     for (int r = 0; r < 16; ++r) p[r] = __builtin_amdgcn_exp2f(p[r]);
;     float ps = 0.f;
; #pragma unroll
;     for (int r = 0; r < 16; ++r) ps += p[r];
;     l_reg += ps; asm volatile("" : "+v"(l_reg));
;     ...
;     ATT_PK4(p, 0, pa0); ATT_PK4(p, 8, pa1);
;     ...
; }
; DI int v_rd_base(int lane) { return ((lane & 3) << 3) | (((lane >> 2) & 3) << 6) | (((lane >> 4) & 1) << 5) | (((lane >> 5) & 1) << 8); }
; template <int OFF> DI s16x4 tr_read(int vb) { s16x4 r; asm volatile("ds_read_b64_tr_b16 %0, %1 offset:%2" : "=&v"(r) : "v"(vb), "i"(OFF) : "memory"); return r; }
; template <int H> DI void v_reads(s16x4* vf, int vb) {
;     vf[0] = tr_read<v_rd_off(0, 2 * H, 0)>(vb); vf[1] = tr_read<v_rd_off(0, 2 * H, 1)>(vb); vf[2] = tr_read<v_rd_off(0, 2 * H + 1, 0)>(vb); vf[3] = tr_read<v_rd_off(0, 2 * H + 1, 1)>(vb);
;     vf[4] = tr_read<v_rd_off(1, 2 * H, 0)>(vb); vf[5] = tr_read<v_rd_off(1, 2 * H, 1)>(vb); vf[6] = tr_read<v_rd_off(1, 2 * H + 1, 0)>(vb); vf[7] = tr_read<v_rd_off(1, 2 * H + 1, 1)>(vb);
;     vf[8] = tr_read<v_rd_off(2, 2 * H, 0)>(vb); vf[9] = tr_read<v_rd_off(2, 2 * H, 1)>(vb); vf[10] = tr_read<v_rd_off(2, 2 * H + 1, 0)>(vb); vf[11] = tr_read<v_rd_off(2, 2 * H + 1, 1)>(vb);
;     vf[12] = tr_read<v_rd_off(3, 2 * H, 0)>(vb); vf[13] = tr_read<v_rd_off(3, 2 * H, 1)>(vb); vf[14] = tr_read<v_rd_off(3, 2 * H + 1, 0)>(vb); vf[15] = tr_read<v_rd_off(3, 2 * H + 1, 1)>(vb);
; }
; DI void pv_mma(f32x16* o, const s16x4* vf, bf16x8 pa0, bf16x8 pa1) {
;     ...
; #pragma unroll
;     for (int d0 = 0; d0 < 4; ++d0) {
;         o[d0] = __builtin_amdgcn_mfma_f32_32x32x16_bf16(pa0, ATT_PK(vf[4 * d0], vf[4 * d0 + 1]), o[d0], 0, 0, 0);
;         o[d0] = __builtin_amdgcn_mfma_f32_32x32x16_bf16(pa1, ATT_PK(vf[4 * d0 + 2], vf[4 * d0 + 3]), o[d0], 0, 0, 0); }
;     ...
; }
; template <int DQK, int D0A, int D0B> DI void k_reads(bf16x8* kf, const LAS unsigned char* Ks, int half, int r32, int hi) {
; #pragma unroll
;     for (int d0 = D0A; d0 < D0B; ++d0) kf[d0 - D0A] = *(const LAS bf16x8*)(Ks + half * (32 * DQK * 2) + kswz<DQK>(r32, (d0 * 16 + hi * 8) * 2));
; }
; template <int D0A, int D0B> DI void qk_mma(f32x16& p, const bf16x8* kf, const bf16x8* qr) {
; #pragma unroll
;     for (int d0 = D0A; d0 < D0B; ++d0) {
.LBB0_1955:
	s_add_i32 s3, s22, 0xffffc000
	s_and_b32 s3, s3, 0x6000
	v_add_u32_e32 v196, s3, v107
	v_add_u32_e32 v197, s3, v108
	v_add_u32_e32 v198, s3, v109
	v_add_u32_e32 v199, s3, v110
	ds_read_b128 v[124:127], v196
	ds_read_b128 v[132:135], v197
	ds_read_b128 v[136:139], v198
	ds_read_b128 v[140:143], v199
	ds_read_b64_tr_b16 v[144:145], v121 offset:0x2000
	ds_read_b64_tr_b16 v[146:147], v121 offset:0x2800
	ds_read_b64_tr_b16 v[148:149], v121 offset:0x3000
	ds_read_b64_tr_b16 v[150:151], v121 offset:0x3800
	ds_read_b64_tr_b16 v[152:153], v121 offset:0x2200
	ds_read_b64_tr_b16 v[154:155], v121 offset:0x2a00
	ds_read_b64_tr_b16 v[156:157], v121 offset:0x3200
	ds_read_b64_tr_b16 v[158:159], v121 offset:0x3a00
	ds_read_b64_tr_b16 v[162:163], v121 offset:0x2400
	ds_read_b64_tr_b16 v[164:165], v121 offset:0x2c00
	ds_read_b64_tr_b16 v[166:167], v121 offset:0x3400
	ds_read_b64_tr_b16 v[168:169], v121 offset:0x3c00
	ds_read_b64_tr_b16 v[170:171], v121 offset:0x2600
	ds_read_b64_tr_b16 v[172:173], v121 offset:0x2e00
	ds_read_b64_tr_b16 v[174:175], v121 offset:0x3600
	ds_read_b64_tr_b16 v[176:177], v121 offset:0x3e00
	s_setprio 2
	v_exp_f32_e32 v64, v64
	v_exp_f32_e32 v65, v65
	v_exp_f32_e32 v66, v66
	v_exp_f32_e32 v67, v67
	v_exp_f32_e32 v68, v68
	v_exp_f32_e32 v69, v69
	v_add_f32_e32 v121, v65, v64
	v_exp_f32_e32 v70, v70
	v_add_f32_e32 v121, v66, v121
	v_exp_f32_e32 v71, v71
	v_add_f32_e32 v121, v67, v121
	v_exp_f32_e32 v72, v72
	v_add_f32_e32 v121, v68, v121
	v_exp_f32_e32 v73, v73
	v_add_f32_e32 v121, v69, v121
	v_exp_f32_e32 v74, v74
	v_add_f32_e32 v121, v70, v121
	v_exp_f32_e32 v75, v75
	v_add_f32_e32 v121, v71, v121
	v_exp_f32_e32 v76, v76
	v_add_f32_e32 v121, v72, v121
	v_exp_f32_e32 v77, v77
	v_add_f32_e32 v121, v73, v121
	v_exp_f32_e32 v78, v78
	v_add_f32_e32 v121, v74, v121
	v_exp_f32_e32 v79, v79
	v_add_f32_e32 v121, v75, v121
	v_add_f32_e32 v121, v76, v121
	v_add_f32_e32 v121, v77, v121
	v_add_f32_e32 v121, v78, v121
	v_add_f32_e32 v121, v79, v121
	v_add_f32_e32 v120, v120, v121
	v_cvt_pk_bf16_f32 v64, v64, v65
	v_cvt_pk_bf16_f32 v65, v66, v67
	v_cvt_pk_bf16_f32 v66, v68, v69
	v_cvt_pk_bf16_f32 v67, v70, v71
	v_cvt_pk_bf16_f32 v68, v72, v73
	v_cvt_pk_bf16_f32 v69, v74, v75
	v_cvt_pk_bf16_f32 v70, v76, v77
	v_cvt_pk_bf16_f32 v71, v78, v79
	s_nop 0
	v_permlane32_swap_b32_e32 v64, v66
	v_permlane32_swap_b32_e32 v65, v67
	v_permlane32_swap_b32_e32 v68, v70
	v_permlane32_swap_b32_e32 v69, v71
	s_waitcnt lgkmcnt(0)
	s_setprio 1
	v_mfma_f32_32x32x16_bf16 v[0:15], v[64:67], v[144:147], v[0:15]
	s_sub_i32 s74, s0, s47
	s_cmp_lt_u32 s74, s100
	v_mfma_f32_32x32x16_bf16 v[48:63], v[64:67], v[152:155], v[48:63]
	v_mfma_f32_32x32x16_bf16 v[16:31], v[64:67], v[162:165], v[16:31]
	v_mfma_f32_32x32x16_bf16 v[32:47], v[64:67], v[170:173], v[32:47]
	v_mfma_f32_32x32x16_bf16 v[0:15], v[68:71], v[148:151], v[0:15]
	v_mfma_f32_32x32x16_bf16 v[48:63], v[68:71], v[156:159], v[48:63]
	v_mfma_f32_32x32x16_bf16 v[16:31], v[68:71], v[166:169], v[16:31]
	v_mfma_f32_32x32x16_bf16 v[32:47], v[68:71], v[174:177], v[32:47]
	v_mfma_f32_32x32x16_bf16 v[64:79], v[124:127], v[92:95], 0
	v_mfma_f32_32x32x16_bf16 v[64:79], v[132:135], v[88:91], v[64:79]
	v_mfma_f32_32x32x16_bf16 v[64:79], v[136:139], v[84:87], v[64:79]
	v_mfma_f32_32x32x16_bf16 v[64:79], v[140:143], v[80:83], v[64:79]
	s_cbranch_scc1 .Ldt_d1_bias2

; #define LAS __attribute__((address_space(3)))
; DI void expsum(f32x16& p, float& l_reg, bf16x8& pa0, bf16x8& pa1) {
; #pragma unroll
;     for (int r = 0; r < 16; ++r) p[r] = __builtin_amdgcn_exp2f(p[r]);
;     float ps = 0.f;
; #pragma unroll
;     for (int r = 0; r < 16; ++r) ps += p[r];
;     l_reg += ps; asm volatile("" : "+v"(l_reg));
;     ...
;     ATT_PK4(p, 0, pa0); ATT_PK4(p, 8, pa1);
;     ...
; }
; DI int v_rd_base(int lane) { return ((lane & 3) << 3) | (((lane >> 2) & 3) << 6) | (((lane >> 4) & 1) << 5) | (((lane >> 5) & 1) << 8); }
; template <int OFF> DI s16x4 tr_read(int vb) { s16x4 r; asm volatile("ds_read_b64_tr_b16 %0, %1 offset:%2" : "=&v"(r) : "v"(vb), "i"(OFF) : "memory"); return r; }
; template <int H> DI void v_reads(s16x4* vf, int vb) {
;     vf[0] = tr_read<v_rd_off(0, 2 * H, 0)>(vb); vf[1] = tr_read<v_rd_off(0, 2 * H, 1)>(vb); vf[2] = tr_read<v_rd_off(0, 2 * H + 1, 0)>(vb); vf[3] = tr_read<v_rd_off(0, 2 * H + 1, 1)>(vb);
;     vf[4] = tr_read<v_rd_off(1, 2 * H, 0)>(vb); vf[5] = tr_read<v_rd_off(1, 2 * H, 1)>(vb); vf[6] = tr_read<v_rd_off(1, 2 * H + 1, 0)>(vb); vf[7] = tr_read<v_rd_off(1, 2 * H + 1, 1)>(vb);
;     vf[8] = tr_read<v_rd_off(2, 2 * H, 0)>(vb); vf[9] = tr_read<v_rd_off(2, 2 * H, 1)>(vb); vf[10] = tr_read<v_rd_off(2, 2 * H + 1, 0)>(vb); vf[11] = tr_read<v_rd_off(2, 2 * H + 1, 1)>(vb);
;     vf[12] = tr_read<v_rd_off(3, 2 * H, 0)>(vb); vf[13] = tr_read<v_rd_off(3, 2 * H, 1)>(vb); vf[14] = tr_read<v_rd_off(3, 2 * H + 1, 0)>(vb); vf[15] = tr_read<v_rd_off(3, 2 * H + 1, 1)>(vb);
; }
; DI void pv_mma(f32x16* o, const s16x4* vf, bf16x8 pa0, bf16x8 pa1) {
;     ...
; #pragma unroll
;     for (int d0 = 0; d0 < 4; ++d0) {
;         o[d0] = __builtin_amdgcn_mfma_f32_32x32x16_bf16(pa0, ATT_PK(vf[4 * d0], vf[4 * d0 + 1]), o[d0], 0, 0, 0);
;         o[d0] = __builtin_amdgcn_mfma_f32_32x32x16_bf16(pa1, ATT_PK(vf[4 * d0 + 2], vf[4 * d0 + 3]), o[d0], 0, 0, 0); }
;     ...
; }
; template <int DQK, int D0A, int D0B> DI void k_reads(bf16x8* kf, const LAS unsigned char* Ks, int half, int r32, int hi) {
; #pragma unroll
;     for (int d0 = D0A; d0 < D0B; ++d0) kf[d0 - D0A] = *(const LAS bf16x8*)(Ks + half * (32 * DQK * 2) + kswz<DQK>(r32, (d0 * 16 + hi * 8) * 2));
; }
; template <int D0A, int D0B> DI void qk_mma(f32x16& p, const bf16x8* kf, const bf16x8* qr) {
; #pragma unroll
;     for (int d0 = D0A; d0 < D0B; ++d0) {
.Lhw_mla_b_n1982:
	s_and_b32 s1, s43, 3
	s_mulk_i32 s1, 0x6000
	s_add_i32 s1, s49, s1
	s_setprio 0
	s_mov_b32 m0, s1
	s_mov_b32 s0, s5
	s_mov_b32 s5, s44
	s_mov_b32 s44, s4
	s_lshl_b32 s4, s4, 14
	global_load_lds_dwordx4 v136, s[34:35]
	s_add_i32 m0, s1, 0x2000
	s_add_i32 s4, s52, s4
	global_load_lds_dwordx4 v138, s[34:35]
	s_add_i32 m0, s1, 0x4000
	s_add_i32 s6, s4, 0x400
	global_load_lds_dwordx4 v140, s[34:35]
	s_mov_b32 m0, s4
	s_add_i32 s1, s43, -3
	global_load_lds_dwordx4 v144, s[34:35]
	s_mov_b32 m0, s6
	s_nop 0
	global_load_lds_dwordx4 v142, s[34:35]
	s_and_b32 s1, s1, 3
	s_mulk_i32 s1, 0x6000
	v_add_u32_e32 v246, s1, v158
	v_add_u32_e32 v250, v246, v151
	v_add_u32_e32 v251, v246, v149
	v_add_u32_e32 v252, v246, v148
	v_add_u32_e32 v253, v246, v147
	s_lshl_b32 s1, s0, 14
	ds_read_b128 v[190:193], v250 offset:12416
	ds_read_b128 v[194:197], v251 offset:12416
	ds_read_b128 v[174:177], v250 offset:12288
	ds_read_b128 v[178:181], v251 offset:12288
	ds_read_b128 v[182:185], v252 offset:12288
	ds_read_b128 v[186:189], v253 offset:12288
	v_add_u32_e32 v254, s1, v130
	ds_read_b64_tr_b16 v[198:199], v254 offset:0
	ds_read_b64_tr_b16 v[200:201], v254 offset:0x800
	ds_read_b64_tr_b16 v[202:203], v254 offset:0x1000
	ds_read_b64_tr_b16 v[204:205], v254 offset:0x1800
	ds_read_b64_tr_b16 v[206:207], v254 offset:0x200
	ds_read_b64_tr_b16 v[208:209], v254 offset:0xa00
	ds_read_b64_tr_b16 v[210:211], v254 offset:0x1200
	ds_read_b64_tr_b16 v[212:213], v254 offset:0x1a00
	ds_read_b64_tr_b16 v[214:215], v254 offset:0x400
	ds_read_b64_tr_b16 v[216:217], v254 offset:0xc00
	ds_read_b64_tr_b16 v[218:219], v254 offset:0x1400
	ds_read_b64_tr_b16 v[220:221], v254 offset:0x1c00
	ds_read_b64_tr_b16 v[222:223], v254 offset:0x600
	ds_read_b64_tr_b16 v[224:225], v254 offset:0xe00
	ds_read_b64_tr_b16 v[226:227], v254 offset:0x1600
	ds_read_b64_tr_b16 v[228:229], v254 offset:0x1e00
	s_setprio 2
	v_exp_f32_e32 v64, v64
	v_exp_f32_e32 v65, v65
	v_exp_f32_e32 v66, v66
	v_exp_f32_e32 v67, v67
	v_exp_f32_e32 v68, v68
	v_exp_f32_e32 v69, v69
	v_add_f32_e32 v230, v65, v64
	v_exp_f32_e32 v70, v70
	v_add_f32_e32 v230, v66, v230
	v_exp_f32_e32 v71, v71
	v_add_f32_e32 v230, v67, v230
	v_exp_f32_e32 v72, v72
	v_add_f32_e32 v230, v68, v230
	v_exp_f32_e32 v73, v73
	v_add_f32_e32 v230, v69, v230
	v_exp_f32_e32 v74, v74
	v_add_f32_e32 v230, v70, v230
	v_exp_f32_e32 v75, v75
	v_add_f32_e32 v230, v71, v230
	v_exp_f32_e32 v76, v76
	v_add_f32_e32 v230, v72, v230
	v_exp_f32_e32 v77, v77
	v_add_f32_e32 v230, v73, v230
	v_exp_f32_e32 v78, v78
	v_add_f32_e32 v230, v74, v230
	v_exp_f32_e32 v79, v79
	v_add_f32_e32 v230, v75, v230
	v_add_f32_e32 v230, v76, v230
	v_add_f32_e32 v230, v77, v230
	v_add_f32_e32 v230, v78, v230
	v_add_f32_e32 v230, v79, v230
	v_add_f32_e32 v173, v173, v230
	v_cvt_pk_bf16_f32 v64, v64, v65
	v_cvt_pk_bf16_f32 v65, v66, v67
	v_cvt_pk_bf16_f32 v66, v68, v69
	v_cvt_pk_bf16_f32 v67, v70, v71
	v_cvt_pk_bf16_f32 v68, v72, v73
	v_cvt_pk_bf16_f32 v69, v74, v75
	v_cvt_pk_bf16_f32 v70, v76, v77
	v_cvt_pk_bf16_f32 v71, v78, v79
	s_nop 0
	v_permlane32_swap_b32_e32 v64, v66
	v_permlane32_swap_b32_e32 v65, v67
	v_permlane32_swap_b32_e32 v68, v70
	v_permlane32_swap_b32_e32 v69, v71
	s_waitcnt lgkmcnt(0)
	ds_read_b128 v[230:233], v252 offset:12416
	ds_read_b128 v[234:237], v253 offset:12416
	ds_read_b128 v[238:241], v250 offset:12544
	ds_read_b128 v[242:245], v251 offset:12544
	ds_read_b128 v[246:249], v252 offset:12544
	ds_read_b128 v[250:253], v253 offset:12544
	s_setprio 1
	v_mfma_f32_32x32x16_bf16 v[48:63], v[64:67], v[198:201], v[48:63]
	v_mfma_f32_32x32x16_bf16 v[32:47], v[64:67], v[206:209], v[32:47]
	v_mfma_f32_32x32x16_bf16 v[16:31], v[64:67], v[214:217], v[16:31]
	v_mfma_f32_32x32x16_bf16 v[0:15], v[64:67], v[222:225], v[0:15]
	v_mfma_f32_32x32x16_bf16 v[48:63], v[68:71], v[202:205], v[48:63]
	v_mfma_f32_32x32x16_bf16 v[32:47], v[68:71], v[210:213], v[32:47]
	v_mfma_f32_32x32x16_bf16 v[16:31], v[68:71], v[218:221], v[16:31]
	v_mfma_f32_32x32x16_bf16 v[0:15], v[68:71], v[226:229], v[0:15]
	s_waitcnt lgkmcnt(0)
	v_mfma_f32_32x32x16_bf16 v[64:79], v[174:177], v[80:83], 0
	v_mfma_f32_32x32x16_bf16 v[64:79], v[178:181], v[84:87], v[64:79]
	v_mfma_f32_32x32x16_bf16 v[64:79], v[182:185], v[88:91], v[64:79]
	v_mfma_f32_32x32x16_bf16 v[64:79], v[186:189], v[92:95], v[64:79]
	v_mfma_f32_32x32x16_bf16 v[64:79], v[190:193], v[96:99], v[64:79]
	v_mfma_f32_32x32x16_bf16 v[64:79], v[194:197], v[100:103], v[64:79]
	v_mfma_f32_32x32x16_bf16 v[64:79], v[230:233], v[104:107], v[64:79]
	v_mfma_f32_32x32x16_bf16 v[64:79], v[234:237], v[108:111], v[64:79]
	v_mfma_f32_32x32x16_bf16 v[64:79], v[238:241], v[112:115], v[64:79]
	v_mfma_f32_32x32x16_bf16 v[64:79], v[242:245], v[116:119], v[64:79]
	v_mfma_f32_32x32x16_bf16 v[64:79], v[246:249], v[120:123], v[64:79]
	v_mfma_f32_32x32x16_bf16 v[64:79], v[250:253], v[124:127], v[64:79]
	s_setprio 0
	s_add_i32 s4, s43, -2
	s_and_b32 s4, s4, 3
	s_mulk_i32 s4, 0x6000
	v_add_u32_e32 v246, s4, v158
	v_add_u32_e32 v250, v246, v151
	v_add_u32_e32 v251, v246, v149
	v_add_u32_e32 v252, v246, v148
	v_add_u32_e32 v253, v246, v147
	ds_read_b128 v[190:193], v250 offset:128
	ds_read_b128 v[194:197], v251 offset:128
	ds_read_b128 v[174:177], v250
	ds_read_b128 v[178:181], v251
	ds_read_b128 v[182:185], v252
	ds_read_b128 v[186:189], v253
	ds_read_b64_tr_b16 v[198:199], v254 offset:0x2000
	ds_read_b64_tr_b16 v[200:201], v254 offset:0x2800
	ds_read_b64_tr_b16 v[202:203], v254 offset:0x3000
	ds_read_b64_tr_b16 v[204:205], v254 offset:0x3800
	ds_read_b64_tr_b16 v[206:207], v254 offset:0x2200
	ds_read_b64_tr_b16 v[208:209], v254 offset:0x2a00
	ds_read_b64_tr_b16 v[210:211], v254 offset:0x3200
; #define LAS __attribute__((address_space(3)))
; DI void expsum(f32x16& p, float& l_reg, bf16x8& pa0, bf16x8& pa1) {
; #pragma unroll
;     for (int r = 0; r < 16; ++r) p[r] = __builtin_amdgcn_exp2f(p[r]);
;     float ps = 0.f;
; #pragma unroll
;     for (int r = 0; r < 16; ++r) ps += p[r];
;     l_reg += ps; asm volatile("" : "+v"(l_reg));
;     ...
;     ATT_PK4(p, 0, pa0); ATT_PK4(p, 8, pa1);
;     ...
; }
; DI int v_rd_base(int lane) { return ((lane & 3) << 3) | (((lane >> 2) & 3) << 6) | (((lane >> 4) & 1) << 5) | (((lane >> 5) & 1) << 8); }
; template <int OFF> DI s16x4 tr_read(int vb) { s16x4 r; asm volatile("ds_read_b64_tr_b16 %0, %1 offset:%2" : "=&v"(r) : "v"(vb), "i"(OFF) : "memory"); return r; }
; template <int H> DI void v_reads(s16x4* vf, int vb) {
;     vf[0] = tr_read<v_rd_off(0, 2 * H, 0)>(vb); vf[1] = tr_read<v_rd_off(0, 2 * H, 1)>(vb); vf[2] = tr_read<v_rd_off(0, 2 * H + 1, 0)>(vb); vf[3] = tr_read<v_rd_off(0, 2 * H + 1, 1)>(vb);
;     vf[4] = tr_read<v_rd_off(1, 2 * H, 0)>(vb); vf[5] = tr_read<v_rd_off(1, 2 * H, 1)>(vb); vf[6] = tr_read<v_rd_off(1, 2 * H + 1, 0)>(vb); vf[7] = tr_read<v_rd_off(1, 2 * H + 1, 1)>(vb);
;     vf[8] = tr_read<v_rd_off(2, 2 * H, 0)>(vb); vf[9] = tr_read<v_rd_off(2, 2 * H, 1)>(vb); vf[10] = tr_read<v_rd_off(2, 2 * H + 1, 0)>(vb); vf[11] = tr_read<v_rd_off(2, 2 * H + 1, 1)>(vb);
;     vf[12] = tr_read<v_rd_off(3, 2 * H, 0)>(vb); vf[13] = tr_read<v_rd_off(3, 2 * H, 1)>(vb); vf[14] = tr_read<v_rd_off(3, 2 * H + 1, 0)>(vb); vf[15] = tr_read<v_rd_off(3, 2 * H + 1, 1)>(vb);
; }
; DI void pv_mma(f32x16* o, const s16x4* vf, bf16x8 pa0, bf16x8 pa1) {
;     ...
; #pragma unroll
;     for (int d0 = 0; d0 < 4; ++d0) {
;         o[d0] = __builtin_amdgcn_mfma_f32_32x32x16_bf16(pa0, ATT_PK(vf[4 * d0], vf[4 * d0 + 1]), o[d0], 0, 0, 0);
;         o[d0] = __builtin_amdgcn_mfma_f32_32x32x16_bf16(pa1, ATT_PK(vf[4 * d0 + 2], vf[4 * d0 + 3]), o[d0], 0, 0, 0); }
;     ...
; }
; template <int DQK, int D0A, int D0B> DI void k_reads(bf16x8* kf, const LAS unsigned char* Ks, int half, int r32, int hi) {
; #pragma unroll
;     for (int d0 = D0A; d0 < D0B; ++d0) kf[d0 - D0A] = *(const LAS bf16x8*)(Ks + half * (32 * DQK * 2) + kswz<DQK>(r32, (d0 * 16 + hi * 8) * 2));
; }
; template <int D0A, int D0B> DI void qk_mma(f32x16& p, const bf16x8* kf, const bf16x8* qr) {
; #pragma unroll
;     for (int d0 = D0A; d0 < D0B; ++d0) {
	ds_read_b64_tr_b16 v[212:213], v254 offset:0x3a00
	ds_read_b64_tr_b16 v[214:215], v254 offset:0x2400
	ds_read_b64_tr_b16 v[216:217], v254 offset:0x2c00
	ds_read_b64_tr_b16 v[218:219], v254 offset:0x3400
	ds_read_b64_tr_b16 v[220:221], v254 offset:0x3c00
	ds_read_b64_tr_b16 v[222:223], v254 offset:0x2600
	ds_read_b64_tr_b16 v[224:225], v254 offset:0x2e00
	ds_read_b64_tr_b16 v[226:227], v254 offset:0x3600
	ds_read_b64_tr_b16 v[228:229], v254 offset:0x3e00
	s_setprio 2
	v_exp_f32_e32 v64, v64
	v_exp_f32_e32 v65, v65
	v_exp_f32_e32 v66, v66
	v_exp_f32_e32 v67, v67
	v_exp_f32_e32 v68, v68
	v_exp_f32_e32 v69, v69
	v_add_f32_e32 v230, v65, v64
	v_exp_f32_e32 v70, v70
	v_add_f32_e32 v230, v66, v230
	v_exp_f32_e32 v71, v71
	v_add_f32_e32 v230, v67, v230
	v_exp_f32_e32 v72, v72
	v_add_f32_e32 v230, v68, v230
	v_exp_f32_e32 v73, v73
	v_add_f32_e32 v230, v69, v230
	v_exp_f32_e32 v74, v74
	v_add_f32_e32 v230, v70, v230
	v_exp_f32_e32 v75, v75
	v_add_f32_e32 v230, v71, v230
	v_exp_f32_e32 v76, v76
	v_add_f32_e32 v230, v72, v230
	v_exp_f32_e32 v77, v77
	v_add_f32_e32 v230, v73, v230
	v_exp_f32_e32 v78, v78
	v_add_f32_e32 v230, v74, v230
	v_exp_f32_e32 v79, v79
	v_add_f32_e32 v230, v75, v230
	v_add_f32_e32 v230, v76, v230
	v_add_f32_e32 v230, v77, v230
	v_add_f32_e32 v230, v78, v230
	v_add_f32_e32 v230, v79, v230
	v_add_f32_e32 v173, v173, v230
	v_cvt_pk_bf16_f32 v64, v64, v65
	v_cvt_pk_bf16_f32 v65, v66, v67
	v_cvt_pk_bf16_f32 v66, v68, v69
	v_cvt_pk_bf16_f32 v67, v70, v71
	v_cvt_pk_bf16_f32 v68, v72, v73
	v_cvt_pk_bf16_f32 v69, v74, v75
	v_cvt_pk_bf16_f32 v70, v76, v77
	v_cvt_pk_bf16_f32 v71, v78, v79
	s_nop 0
	v_permlane32_swap_b32_e32 v64, v66
	v_permlane32_swap_b32_e32 v65, v67
	v_permlane32_swap_b32_e32 v68, v70
	v_permlane32_swap_b32_e32 v69, v71
	s_waitcnt lgkmcnt(0)
	ds_read_b128 v[230:233], v252 offset:128
	ds_read_b128 v[234:237], v253 offset:128
	ds_read_b128 v[238:241], v250 offset:256
	ds_read_b128 v[242:245], v251 offset:256
	ds_read_b128 v[246:249], v252 offset:256
	ds_read_b128 v[250:253], v253 offset:256
	s_setprio 1
	s_waitcnt vmcnt(5)
	s_barrier
	v_mfma_f32_32x32x16_bf16 v[48:63], v[64:67], v[198:201], v[48:63]
	v_mfma_f32_32x32x16_bf16 v[32:47], v[64:67], v[206:209], v[32:47]
	v_mfma_f32_32x32x16_bf16 v[16:31], v[64:67], v[214:217], v[16:31]
	v_mfma_f32_32x32x16_bf16 v[0:15], v[64:67], v[222:225], v[0:15]
	v_mfma_f32_32x32x16_bf16 v[48:63], v[68:71], v[202:205], v[48:63]
	v_mfma_f32_32x32x16_bf16 v[32:47], v[68:71], v[210:213], v[32:47]
	v_mfma_f32_32x32x16_bf16 v[16:31], v[68:71], v[218:221], v[16:31]
	v_mfma_f32_32x32x16_bf16 v[0:15], v[68:71], v[226:229], v[0:15]
	s_waitcnt lgkmcnt(0)
	v_mfma_f32_32x32x16_bf16 v[64:79], v[174:177], v[80:83], 0
	v_mfma_f32_32x32x16_bf16 v[64:79], v[178:181], v[84:87], v[64:79]
	v_mfma_f32_32x32x16_bf16 v[64:79], v[182:185], v[88:91], v[64:79]
	v_mfma_f32_32x32x16_bf16 v[64:79], v[186:189], v[92:95], v[64:79]
	v_mfma_f32_32x32x16_bf16 v[64:79], v[190:193], v[96:99], v[64:79]
	v_mfma_f32_32x32x16_bf16 v[64:79], v[194:197], v[100:103], v[64:79]
	v_mfma_f32_32x32x16_bf16 v[64:79], v[230:233], v[104:107], v[64:79]
	v_mfma_f32_32x32x16_bf16 v[64:79], v[234:237], v[108:111], v[64:79]
	v_mfma_f32_32x32x16_bf16 v[64:79], v[238:241], v[112:115], v[64:79]
	v_mfma_f32_32x32x16_bf16 v[64:79], v[242:245], v[116:119], v[64:79]
	v_mfma_f32_32x32x16_bf16 v[64:79], v[246:249], v[120:123], v[64:79]
	v_mfma_f32_32x32x16_bf16 v[64:79], v[250:253], v[124:127], v[64:79]
	s_add_i32 s43, s43, 1
	v_add_u32_e32 v136, s36, v136
	v_add_u32_e32 v138, s36, v138
	v_add_u32_e32 v140, s36, v140
	v_add_u32_e32 v142, s38, v142
	v_add_u32_e32 v144, s38, v144
	s_cmp_eq_u32 s43, 64
	s_mov_b32 s4, s0
	s_cbranch_scc0 .Lhw_mla_b_n1982
	s_branch .Lhw_mla_exit
.LBB0_1982:
	s_and_b32 s1, s43, 3
	s_mulk_i32 s1, 0x6000
	s_add_i32 s1, s49, s1
	s_waitcnt vmcnt(5)
	s_barrier
	s_setprio 0
	s_mov_b32 m0, s1
	s_mov_b32 s0, s5
	s_mov_b32 s5, s44
	s_mov_b32 s44, s4
	s_lshl_b32 s4, s4, 14
	global_load_lds_dwordx4 v136, s[34:35]
	s_add_i32 m0, s1, 0x2000
	s_add_i32 s4, s52, s4
	global_load_lds_dwordx4 v138, s[34:35]
	s_add_i32 m0, s1, 0x4000
	s_add_i32 s6, s4, 0x400
	global_load_lds_dwordx4 v140, s[34:35]
	s_mov_b32 m0, s4
	s_add_i32 s1, s43, -3
	global_load_lds_dwordx4 v144, s[34:35]
	s_mov_b32 m0, s6
	s_nop 0
	global_load_lds_dwordx4 v142, s[34:35]
	s_and_b32 s1, s1, 3
	s_mulk_i32 s1, 0x6000
	v_add_u32_e32 v246, s1, v158
	v_add_u32_e32 v250, v246, v151
	v_add_u32_e32 v251, v246, v149
	v_add_u32_e32 v252, v246, v148
	v_add_u32_e32 v253, v246, v147
	s_lshl_b32 s1, s0, 14
	ds_read_b128 v[190:193], v250 offset:12416
	ds_read_b128 v[194:197], v251 offset:12416
	ds_read_b128 v[174:177], v250 offset:12288
	ds_read_b128 v[178:181], v251 offset:12288
	ds_read_b128 v[182:185], v252 offset:12288
	ds_read_b128 v[186:189], v253 offset:12288
	v_add_u32_e32 v254, s1, v130
	ds_read_b64_tr_b16 v[198:199], v254 offset:0
	ds_read_b64_tr_b16 v[200:201], v254 offset:0x800
	ds_read_b64_tr_b16 v[202:203], v254 offset:0x1000
	ds_read_b64_tr_b16 v[204:205], v254 offset:0x1800
	ds_read_b64_tr_b16 v[206:207], v254 offset:0x200
	ds_read_b64_tr_b16 v[208:209], v254 offset:0xa00
	ds_read_b64_tr_b16 v[210:211], v254 offset:0x1200
	ds_read_b64_tr_b16 v[212:213], v254 offset:0x1a00
	ds_read_b64_tr_b16 v[214:215], v254 offset:0x400
	ds_read_b64_tr_b16 v[216:217], v254 offset:0xc00
	ds_read_b64_tr_b16 v[218:219], v254 offset:0x1400
	ds_read_b64_tr_b16 v[220:221], v254 offset:0x1c00
	ds_read_b64_tr_b16 v[222:223], v254 offset:0x600
	ds_read_b64_tr_b16 v[224:225], v254 offset:0xe00
	ds_read_b64_tr_b16 v[226:227], v254 offset:0x1600
	ds_read_b64_tr_b16 v[228:229], v254 offset:0x1e00
	s_setprio 2
	v_exp_f32_e32 v64, v64
	v_exp_f32_e32 v65, v65
	v_exp_f32_e32 v66, v66
	v_exp_f32_e32 v67, v67
	v_exp_f32_e32 v68, v68
	v_exp_f32_e32 v69, v69
	v_add_f32_e32 v230, v65, v64
	v_exp_f32_e32 v70, v70
	v_add_f32_e32 v230, v66, v230
	v_exp_f32_e32 v71, v71
	v_add_f32_e32 v230, v67, v230
	v_exp_f32_e32 v72, v72
	v_add_f32_e32 v230, v68, v230
	v_exp_f32_e32 v73, v73
	v_add_f32_e32 v230, v69, v230
	v_exp_f32_e32 v74, v74
	v_add_f32_e32 v230, v70, v230
	v_exp_f32_e32 v75, v75
	v_add_f32_e32 v230, v71, v230
	v_exp_f32_e32 v76, v76
	v_add_f32_e32 v230, v72, v230
	v_exp_f32_e32 v77, v77
	v_add_f32_e32 v230, v73, v230
	v_exp_f32_e32 v78, v78
	v_add_f32_e32 v230, v74, v230
	v_exp_f32_e32 v79, v79
	v_add_f32_e32 v230, v75, v230
	v_add_f32_e32 v230, v76, v230
	v_add_f32_e32 v230, v77, v230
	v_add_f32_e32 v230, v78, v230
	v_add_f32_e32 v230, v79, v230
	v_add_f32_e32 v173, v173, v230
	v_cvt_pk_bf16_f32 v64, v64, v65
	v_cvt_pk_bf16_f32 v65, v66, v67
	v_cvt_pk_bf16_f32 v66, v68, v69
	v_cvt_pk_bf16_f32 v67, v70, v71
	v_cvt_pk_bf16_f32 v68, v72, v73
	v_cvt_pk_bf16_f32 v69, v74, v75
	v_cvt_pk_bf16_f32 v70, v76, v77
	v_cvt_pk_bf16_f32 v71, v78, v79
	s_nop 0
	v_permlane32_swap_b32_e32 v64, v66
	v_permlane32_swap_b32_e32 v65, v67
	v_permlane32_swap_b32_e32 v68, v70
	v_permlane32_swap_b32_e32 v69, v71
	s_waitcnt lgkmcnt(0)
; #define LAS __attribute__((address_space(3)))
; DI void expsum(f32x16& p, float& l_reg, bf16x8& pa0, bf16x8& pa1) {
; #pragma unroll
;     for (int r = 0; r < 16; ++r) p[r] = __builtin_amdgcn_exp2f(p[r]);
;     float ps = 0.f;
; #pragma unroll
;     for (int r = 0; r < 16; ++r) ps += p[r];
;     l_reg += ps; asm volatile("" : "+v"(l_reg));
;     ...
;     ATT_PK4(p, 0, pa0); ATT_PK4(p, 8, pa1);
;     ...
; }
; DI int v_rd_base(int lane) { return ((lane & 3) << 3) | (((lane >> 2) & 3) << 6) | (((lane >> 4) & 1) << 5) | (((lane >> 5) & 1) << 8); }
; template <int OFF> DI s16x4 tr_read(int vb) { s16x4 r; asm volatile("ds_read_b64_tr_b16 %0, %1 offset:%2" : "=&v"(r) : "v"(vb), "i"(OFF) : "memory"); return r; }
; template <int H> DI void v_reads(s16x4* vf, int vb) {
;     vf[0] = tr_read<v_rd_off(0, 2 * H, 0)>(vb); vf[1] = tr_read<v_rd_off(0, 2 * H, 1)>(vb); vf[2] = tr_read<v_rd_off(0, 2 * H + 1, 0)>(vb); vf[3] = tr_read<v_rd_off(0, 2 * H + 1, 1)>(vb);
;     vf[4] = tr_read<v_rd_off(1, 2 * H, 0)>(vb); vf[5] = tr_read<v_rd_off(1, 2 * H, 1)>(vb); vf[6] = tr_read<v_rd_off(1, 2 * H + 1, 0)>(vb); vf[7] = tr_read<v_rd_off(1, 2 * H + 1, 1)>(vb);
;     vf[8] = tr_read<v_rd_off(2, 2 * H, 0)>(vb); vf[9] = tr_read<v_rd_off(2, 2 * H, 1)>(vb); vf[10] = tr_read<v_rd_off(2, 2 * H + 1, 0)>(vb); vf[11] = tr_read<v_rd_off(2, 2 * H + 1, 1)>(vb);
;     vf[12] = tr_read<v_rd_off(3, 2 * H, 0)>(vb); vf[13] = tr_read<v_rd_off(3, 2 * H, 1)>(vb); vf[14] = tr_read<v_rd_off(3, 2 * H + 1, 0)>(vb); vf[15] = tr_read<v_rd_off(3, 2 * H + 1, 1)>(vb);
; }
; DI void pv_mma(f32x16* o, const s16x4* vf, bf16x8 pa0, bf16x8 pa1) {
;     ...
; #pragma unroll
;     for (int d0 = 0; d0 < 4; ++d0) {
;         o[d0] = __builtin_amdgcn_mfma_f32_32x32x16_bf16(pa0, ATT_PK(vf[4 * d0], vf[4 * d0 + 1]), o[d0], 0, 0, 0);
;         o[d0] = __builtin_amdgcn_mfma_f32_32x32x16_bf16(pa1, ATT_PK(vf[4 * d0 + 2], vf[4 * d0 + 3]), o[d0], 0, 0, 0); }
;     ...
; }
; template <int DQK, int D0A, int D0B> DI void k_reads(bf16x8* kf, const LAS unsigned char* Ks, int half, int r32, int hi) {
; #pragma unroll
;     for (int d0 = D0A; d0 < D0B; ++d0) kf[d0 - D0A] = *(const LAS bf16x8*)(Ks + half * (32 * DQK * 2) + kswz<DQK>(r32, (d0 * 16 + hi * 8) * 2));
; }
; template <int D0A, int D0B> DI void qk_mma(f32x16& p, const bf16x8* kf, const bf16x8* qr) {
; #pragma unroll
;     for (int d0 = D0A; d0 < D0B; ++d0) {
	ds_read_b128 v[230:233], v252 offset:12416
	ds_read_b128 v[234:237], v253 offset:12416
	ds_read_b128 v[238:241], v250 offset:12544
	ds_read_b128 v[242:245], v251 offset:12544
	ds_read_b128 v[246:249], v252 offset:12544
	ds_read_b128 v[250:253], v253 offset:12544
	s_setprio 1
	v_mfma_f32_32x32x16_bf16 v[48:63], v[64:67], v[198:201], v[48:63]
	v_mfma_f32_32x32x16_bf16 v[32:47], v[64:67], v[206:209], v[32:47]
	v_mfma_f32_32x32x16_bf16 v[16:31], v[64:67], v[214:217], v[16:31]
	v_mfma_f32_32x32x16_bf16 v[0:15], v[64:67], v[222:225], v[0:15]
	v_mfma_f32_32x32x16_bf16 v[48:63], v[68:71], v[202:205], v[48:63]
	v_mfma_f32_32x32x16_bf16 v[32:47], v[68:71], v[210:213], v[32:47]
	v_mfma_f32_32x32x16_bf16 v[16:31], v[68:71], v[218:221], v[16:31]
	v_mfma_f32_32x32x16_bf16 v[0:15], v[68:71], v[226:229], v[0:15]
	s_waitcnt lgkmcnt(0)
	v_mfma_f32_32x32x16_bf16 v[64:79], v[174:177], v[80:83], 0
	v_mfma_f32_32x32x16_bf16 v[64:79], v[178:181], v[84:87], v[64:79]
	v_mfma_f32_32x32x16_bf16 v[64:79], v[182:185], v[88:91], v[64:79]
	v_mfma_f32_32x32x16_bf16 v[64:79], v[186:189], v[92:95], v[64:79]
	v_mfma_f32_32x32x16_bf16 v[64:79], v[190:193], v[96:99], v[64:79]
	v_mfma_f32_32x32x16_bf16 v[64:79], v[194:197], v[100:103], v[64:79]
	v_mfma_f32_32x32x16_bf16 v[64:79], v[230:233], v[104:107], v[64:79]
	v_mfma_f32_32x32x16_bf16 v[64:79], v[234:237], v[108:111], v[64:79]
	v_mfma_f32_32x32x16_bf16 v[64:79], v[238:241], v[112:115], v[64:79]
	v_mfma_f32_32x32x16_bf16 v[64:79], v[242:245], v[116:119], v[64:79]
	v_mfma_f32_32x32x16_bf16 v[64:79], v[246:249], v[120:123], v[64:79]
	v_mfma_f32_32x32x16_bf16 v[64:79], v[250:253], v[124:127], v[64:79]
	s_setprio 0
	s_add_i32 s4, s43, -2
	s_and_b32 s4, s4, 3
	s_mulk_i32 s4, 0x6000
	v_add_u32_e32 v246, s4, v158
	v_add_u32_e32 v250, v246, v151
	v_add_u32_e32 v251, v246, v149
	v_add_u32_e32 v252, v246, v148
	v_add_u32_e32 v253, v246, v147
	ds_read_b128 v[190:193], v250 offset:128
	ds_read_b128 v[194:197], v251 offset:128
	ds_read_b128 v[174:177], v250
	ds_read_b128 v[178:181], v251
	ds_read_b128 v[182:185], v252
	ds_read_b128 v[186:189], v253
	ds_read_b64_tr_b16 v[198:199], v254 offset:0x2000
	ds_read_b64_tr_b16 v[200:201], v254 offset:0x2800
	ds_read_b64_tr_b16 v[202:203], v254 offset:0x3000
	ds_read_b64_tr_b16 v[204:205], v254 offset:0x3800
	ds_read_b64_tr_b16 v[206:207], v254 offset:0x2200
	ds_read_b64_tr_b16 v[208:209], v254 offset:0x2a00
	ds_read_b64_tr_b16 v[210:211], v254 offset:0x3200
	ds_read_b64_tr_b16 v[212:213], v254 offset:0x3a00
	ds_read_b64_tr_b16 v[214:215], v254 offset:0x2400
	ds_read_b64_tr_b16 v[216:217], v254 offset:0x2c00
	ds_read_b64_tr_b16 v[218:219], v254 offset:0x3400
	ds_read_b64_tr_b16 v[220:221], v254 offset:0x3c00
	ds_read_b64_tr_b16 v[222:223], v254 offset:0x2600
	ds_read_b64_tr_b16 v[224:225], v254 offset:0x2e00
	ds_read_b64_tr_b16 v[226:227], v254 offset:0x3600
	ds_read_b64_tr_b16 v[228:229], v254 offset:0x3e00
	s_setprio 2
	v_exp_f32_e32 v64, v64
	v_exp_f32_e32 v65, v65
	v_exp_f32_e32 v66, v66
	v_exp_f32_e32 v67, v67
	v_exp_f32_e32 v68, v68
	v_exp_f32_e32 v69, v69
	v_add_f32_e32 v230, v65, v64
	v_exp_f32_e32 v70, v70
	v_add_f32_e32 v230, v66, v230
	v_exp_f32_e32 v71, v71
	v_add_f32_e32 v230, v67, v230
	v_exp_f32_e32 v72, v72
	v_add_f32_e32 v230, v68, v230
	v_exp_f32_e32 v73, v73
	v_add_f32_e32 v230, v69, v230
	v_exp_f32_e32 v74, v74
	v_add_f32_e32 v230, v70, v230
	v_exp_f32_e32 v75, v75
	v_add_f32_e32 v230, v71, v230
	v_exp_f32_e32 v76, v76
	v_add_f32_e32 v230, v72, v230
	v_exp_f32_e32 v77, v77
	v_add_f32_e32 v230, v73, v230
	v_exp_f32_e32 v78, v78
	v_add_f32_e32 v230, v74, v230
	v_exp_f32_e32 v79, v79
	v_add_f32_e32 v230, v75, v230
	v_add_f32_e32 v230, v76, v230
	v_add_f32_e32 v230, v77, v230
	v_add_f32_e32 v230, v78, v230
	v_add_f32_e32 v230, v79, v230
	v_add_f32_e32 v173, v173, v230
	v_cvt_pk_bf16_f32 v64, v64, v65
	v_cvt_pk_bf16_f32 v65, v66, v67
	v_cvt_pk_bf16_f32 v66, v68, v69
	v_cvt_pk_bf16_f32 v67, v70, v71
	v_cvt_pk_bf16_f32 v68, v72, v73
	v_cvt_pk_bf16_f32 v69, v74, v75
	v_cvt_pk_bf16_f32 v70, v76, v77
	v_cvt_pk_bf16_f32 v71, v78, v79
	s_nop 0
	v_permlane32_swap_b32_e32 v64, v66
	v_permlane32_swap_b32_e32 v65, v67
	v_permlane32_swap_b32_e32 v68, v70
	v_permlane32_swap_b32_e32 v69, v71
	s_waitcnt lgkmcnt(0)
	ds_read_b128 v[230:233], v252 offset:128
	ds_read_b128 v[234:237], v253 offset:128
	ds_read_b128 v[238:241], v250 offset:256
	ds_read_b128 v[242:245], v251 offset:256
	ds_read_b128 v[246:249], v252 offset:256
	ds_read_b128 v[250:253], v253 offset:256
	s_setprio 1
	v_mfma_f32_32x32x16_bf16 v[48:63], v[64:67], v[198:201], v[48:63]
	v_mfma_f32_32x32x16_bf16 v[32:47], v[64:67], v[206:209], v[32:47]
	v_mfma_f32_32x32x16_bf16 v[16:31], v[64:67], v[214:217], v[16:31]
	v_mfma_f32_32x32x16_bf16 v[0:15], v[64:67], v[222:225], v[0:15]
	v_mfma_f32_32x32x16_bf16 v[48:63], v[68:71], v[202:205], v[48:63]
	v_mfma_f32_32x32x16_bf16 v[32:47], v[68:71], v[210:213], v[32:47]
	v_mfma_f32_32x32x16_bf16 v[16:31], v[68:71], v[218:221], v[16:31]
	v_mfma_f32_32x32x16_bf16 v[0:15], v[68:71], v[226:229], v[0:15]
	s_waitcnt lgkmcnt(0)
	v_mfma_f32_32x32x16_bf16 v[64:79], v[174:177], v[80:83], 0
	v_mfma_f32_32x32x16_bf16 v[64:79], v[178:181], v[84:87], v[64:79]
	v_mfma_f32_32x32x16_bf16 v[64:79], v[182:185], v[88:91], v[64:79]
	v_mfma_f32_32x32x16_bf16 v[64:79], v[186:189], v[92:95], v[64:79]
	v_mfma_f32_32x32x16_bf16 v[64:79], v[190:193], v[96:99], v[64:79]
	v_mfma_f32_32x32x16_bf16 v[64:79], v[194:197], v[100:103], v[64:79]
	v_mfma_f32_32x32x16_bf16 v[64:79], v[230:233], v[104:107], v[64:79]
	v_mfma_f32_32x32x16_bf16 v[64:79], v[234:237], v[108:111], v[64:79]
	v_mfma_f32_32x32x16_bf16 v[64:79], v[238:241], v[112:115], v[64:79]
	v_mfma_f32_32x32x16_bf16 v[64:79], v[242:245], v[116:119], v[64:79]
	v_mfma_f32_32x32x16_bf16 v[64:79], v[246:249], v[120:123], v[64:79]
	v_mfma_f32_32x32x16_bf16 v[64:79], v[250:253], v[124:127], v[64:79]
	s_add_i32 s43, s43, 1
	v_add_u32_e32 v136, s36, v136
	v_add_u32_e32 v138, s36, v138
	v_add_u32_e32 v140, s36, v140
	v_add_u32_e32 v142, s38, v142
	v_add_u32_e32 v144, s38, v144
	s_cmp_eq_u32 s43, 64
	s_mov_b32 s4, s0
	s_cbranch_scc0 .LBB0_1982
.Lhw_mla_exit:
	s_lshl_b32 s0, s55, 2
	s_add_i32 s4, s0, 0
	s_add_i32 s6, s52, s1
	s_add_i32 s4, s4, 0x24000
	s_add_i32 s7, s6, 0x400
	s_add_u32 s0, s2, 0x3f0000
	s_addc_u32 s1, s3, 0
	s_cmp_lt_u32 s33, 0x100
	s_cbranch_scc0 .Lstg_mla_t61_4
	s_waitcnt vmcnt(5)
	s_barrier
